# token-MLP item: software prefetch of the next item's v_n/u tiles into L2 (one dword per 128B line) after own loads land; placement kept at +4 mod 64
# speedup vs baseline: 1.0038x; 1.0038x over previous
; __device__ __forceinline__ void mlp_tile(const Ctx& C, int l, int ct, int hd) {
;     ...
;         for (int sw = 0; sw < 4; ++sw) { const int s = sw * 32 + (tid >> 4);
;             vv[sw] = *(const u32x4*)(vn + (size_t)(T.row0 + min(s, T.nvalid - 1)) * GW + hd * 128 + d8); }
; #pragma unroll
;         for (int sw = 0; sw < 4; ++sw) { const int s = sw * 32 + (tid >> 4); if (s >= T.nvalid) vv[sw] = (u32x4){0u, 0u, 0u, 0u}; }
; __global__ void __launch_bounds__(NTHREADS, 2) mega(Args a) {
;     ...
;             for (int it = C.bid; it < 2 * NCT * 8; it += C.G) {
;                 if (it < 128 * 8) lru_fix_tile(C, l, it >> 3, it & 7); else if (it < NCT * 8) { LruHead H; load_lru_head(C, l, it & 7, H); lru_tile<2>(C, l, it >> 3, it & 7, H); } else mlp_tile(C, l, (it - NCT * 8) >> 3, it & 7);
.LBB0_916:
	v_sub_u32_e32 v0, s2, v110
	v_cmp_lt_i32_e32 vcc, 0, v0
	s_movk_i32 s2, 0x60
	s_waitcnt vmcnt(3)
	v_cndmask_b32_e32 v9, 0, v9, vcc
	v_cndmask_b32_e32 v8, 0, v8, vcc
	v_cndmask_b32_e32 v7, 0, v7, vcc
	v_cndmask_b32_e32 v6, 0, v6, vcc
	v_cmp_lt_i32_e32 vcc, 32, v0
	s_waitcnt vmcnt(2)
	s_nop 0
	v_cndmask_b32_e32 v5, 0, v5, vcc
	v_cndmask_b32_e32 v4, 0, v4, vcc
	v_cndmask_b32_e32 v3, 0, v3, vcc
	v_cndmask_b32_e32 v2, 0, v2, vcc
	v_cmp_lt_i32_e32 vcc, 64, v0
	s_waitcnt vmcnt(1)
	s_nop 0
	v_cndmask_b32_e32 v17, 0, v17, vcc
	v_cndmask_b32_e32 v16, 0, v16, vcc
	v_cndmask_b32_e32 v15, 0, v15, vcc
	v_cndmask_b32_e32 v14, 0, v14, vcc
	v_cmp_lt_i32_e32 vcc, s2, v0
	s_waitcnt vmcnt(0)
	s_nop 0
	v_cndmask_b32_e32 v0, 0, v13, vcc
	v_cndmask_b32_e32 v12, 0, v12, vcc
	v_cndmask_b32_e32 v11, 0, v11, vcc
	v_cndmask_b32_e32 v10, 0, v10, vcc
	s_add_i32 s2, s67, s74
	s_cmpk_lt_i32 s2, 0x900
	s_cbranch_scc0 .Lmy_pf_skip
	s_addk_i32 s2, 0xfb80
	s_and_b32 s3, s2, 7
	s_lshl_b32 s3, s3, 8
	s_lshr_b32 s2, s2, 3
	s_lshl_b32 s100, s2, 7
	s_lshl_b32 s101, s2, 6
	s_addk_i32 s101, 0x2000
	s_cmpk_lt_u32 s2, 0x80
	s_cselect_b32 s100, s100, s101
	v_and_b32_e32 v216, 0xff, v220
	v_lshrrev_b32_e32 v217, 1, v216
	v_and_b32_e32 v216, 1, v216
	v_lshlrev_b32_e32 v216, 7, v216
	v_add_u32_e32 v217, s100, v217
	v_lshrrev_b32_e32 v218, 8, v220
	v_lshlrev_b32_e32 v219, 1, v218
	v_lshlrev_b32_e32 v217, 11, v217
	v_lshlrev_b32_e32 v217, v219, v217
	v_lshl_add_u32 v217, v218, 12, v217
	v_add3_u32 v217, v217, v216, s3
	v_mul_u32_u24_e32 v218, 0x88, v218
	v_lshlrev_b32_e32 v218, 20, v218
	v_sub_u32_e32 v217, v217, v218
	v_add_u32_e32 v217, 0x12a00000, v217
	global_load_dword v215, v217, s[90:91]
; #define LAS __attribute__((address_space(3)))
; __device__ __forceinline__ void mlp_tile(const Ctx& C, int l, int ct, int hd) {
;     ...
;         for (int sw = 0; sw < 4; ++sw) { const int s = sw * 32 + (tid >> 4); const u32x4 v = vv[sw];
;             const int sc = ((((s >> 3) ^ (tid & 15)) << 3) | (s & 7));
;             VT[(d8 + 0) * SX + sc] = (bf16_t)(v.x & 0xffffu); VT[(d8 + 1) * SX + sc] = (bf16_t)(v.x >> 16);
;             VT[(d8 + 2) * SX + sc] = (bf16_t)(v.y & 0xffffu); VT[(d8 + 3) * SX + sc] = (bf16_t)(v.y >> 16);
;             VT[(d8 + 4) * SX + sc] = (bf16_t)(v.z & 0xffffu); VT[(d8 + 5) * SX + sc] = (bf16_t)(v.z >> 16);
;             VT[(d8 + 6) * SX + sc] = (bf16_t)(v.w & 0xffffu); VT[(d8 + 7) * SX + sc] = (bf16_t)(v.w >> 16);
;         }
;     }
;     __syncthreads();
;     if (wact) {
;         const int nk = ((16 * w + 15) >> 5) + 1;
;         f32x4 acc[8];
; #pragma unroll
;         for (int n = 0; n < 8; ++n) acc[n] = (f32x4){0.f, 0.f, 0.f, 0.f};
; #pragma unroll
;         for (int kk = 0; kk < 4; ++kk) {
;             if (kk >= nk) break;
;             const bf16x8 wf = wfr[kk];
; #pragma unroll
;             for (int n = 0; n < 8; ++n) { const bf16x8 vf = *(const LAS bf16x8*)(VT + (16 * n + fr) * SX + (((4 * kk + fq) ^ (2 * n + (fr >> 3))) << 3));
;                 acc[n] = __builtin_amdgcn_mfma_f32_16x16x32_bf16(vf, wf, acc[n], 0, 0, 0); }
;         }
.Lmy_pf_skip:
	s_andn2_b64 vcc, exec, s[22:23]
	ds_write_b16 v134, v6
	ds_write_b16_d16_hi v134, v6 offset:272
	ds_write_b16 v134, v7 offset:544
	ds_write_b16_d16_hi v134, v7 offset:816
	ds_write_b16 v134, v8 offset:1088
	ds_write_b16_d16_hi v134, v8 offset:1360
	ds_write_b16 v134, v9 offset:1632
	ds_write_b16_d16_hi v134, v9 offset:1904
	ds_write_b16 v135, v2
	ds_write_b16_d16_hi v135, v2 offset:272
	ds_write_b16 v135, v3 offset:544
	ds_write_b16_d16_hi v135, v3 offset:816
	ds_write_b16 v135, v4 offset:1088
	ds_write_b16_d16_hi v135, v4 offset:1360
	ds_write_b16 v135, v5 offset:1632
	ds_write_b16_d16_hi v135, v5 offset:1904
	ds_write_b16 v136, v14
	ds_write_b16_d16_hi v136, v14 offset:272
	ds_write_b16 v136, v15 offset:544
	ds_write_b16_d16_hi v136, v15 offset:816
	ds_write_b16 v136, v16 offset:1088
	ds_write_b16_d16_hi v136, v16 offset:1360
	ds_write_b16 v136, v17 offset:1632
	ds_write_b16_d16_hi v136, v17 offset:1904
	ds_write_b16 v137, v10
	ds_write_b16_d16_hi v137, v10 offset:272
	ds_write_b16 v137, v11 offset:544
	ds_write_b16_d16_hi v137, v11 offset:816
	ds_write_b16 v137, v12 offset:1088
	ds_write_b16_d16_hi v137, v12 offset:1360
	ds_write_b16 v137, v0 offset:1632
	ds_write_b16_d16_hi v137, v0 offset:1904
	s_waitcnt lgkmcnt(0)
	s_barrier
	s_cbranch_vccnz .LBB0_925
	v_readlane_b32 s2, v249, 55
	v_readlane_b32 s3, v249, 56
	v_mov_b32_e32 v30, 0
	s_andn2_b64 vcc, exec, s[2:3]
	v_mov_b32_e32 v31, 0
	v_mov_b32_e32 v32, 0
	v_mov_b32_e32 v33, 0
	v_mov_b32_e32 v26, 0
	v_mov_b32_e32 v27, 0
	v_mov_b32_e32 v28, 0
	v_mov_b32_e32 v29, 0
	v_mov_b32_e32 v22, 0
	v_mov_b32_e32 v23, 0
	v_mov_b32_e32 v24, 0
	v_mov_b32_e32 v25, 0
	v_mov_b32_e32 v18, 0
	v_mov_b32_e32 v19, 0
	v_mov_b32_e32 v20, 0
	v_mov_b32_e32 v21, 0
	v_mov_b32_e32 v14, 0
	v_mov_b32_e32 v15, 0
	v_mov_b32_e32 v16, 0
	v_mov_b32_e32 v17, 0
	v_mov_b32_e32 v10, 0
	v_mov_b32_e32 v11, 0
	v_mov_b32_e32 v12, 0
	v_mov_b32_e32 v13, 0
	v_mov_b32_e32 v6, 0
	v_mov_b32_e32 v7, 0
	v_mov_b32_e32 v8, 0
	v_mov_b32_e32 v9, 0
	v_mov_b32_e32 v2, 0
	v_mov_b32_e32 v3, 0
	v_mov_b32_e32 v4, 0
	v_mov_b32_e32 v5, 0
	s_cbranch_vccnz .LBB0_922
	ds_read_b128 v[2:5], v144
	ds_read_b128 v[6:9], v145 offset:4352
	v_readlane_b32 s2, v249, 57
	v_readlane_b32 s3, v249, 58
	s_andn2_b64 vcc, exec, s[2:3]
	s_waitcnt lgkmcnt(1)
	v_mfma_f32_16x16x32_bf16 v[30:33], v[2:5], v[46:49], 0
	ds_read_b128 v[2:5], v146 offset:8704
	ds_read_b128 v[70:73], v151 offset:30464
	s_waitcnt lgkmcnt(2)
	v_mfma_f32_16x16x32_bf16 v[26:29], v[6:9], v[46:49], 0
	ds_read_b128 v[6:9], v147 offset:13056
	s_waitcnt lgkmcnt(2)
	v_mfma_f32_16x16x32_bf16 v[22:25], v[2:5], v[46:49], 0
	ds_read_b128 v[2:5], v148 offset:17408
	s_waitcnt lgkmcnt(1)
	v_mfma_f32_16x16x32_bf16 v[18:21], v[6:9], v[46:49], 0
	ds_read_b128 v[6:9], v149 offset:21760
	s_waitcnt lgkmcnt(1)
	v_mfma_f32_16x16x32_bf16 v[14:17], v[2:5], v[46:49], 0
	ds_read_b128 v[2:5], v150 offset:26112
	s_waitcnt lgkmcnt(1)
	v_mfma_f32_16x16x32_bf16 v[10:13], v[6:9], v[46:49], 0
	s_waitcnt lgkmcnt(0)
	v_mfma_f32_16x16x32_bf16 v[6:9], v[2:5], v[46:49], 0
	v_mfma_f32_16x16x32_bf16 v[2:5], v[70:73], v[46:49], 0
	s_cbranch_vccnz .LBB0_922
	ds_read_b128 v[232:235], v152
	ds_read_b128 v[236:239], v153 offset:4352
	ds_read_b128 v[240:243], v154 offset:8704
	ds_read_b128 v[244:247], v155 offset:13056
	v_readlane_b32 s2, v249, 59
	v_readlane_b32 s3, v249, 60
	s_andn2_b64 vcc, exec, s[2:3]
	s_waitcnt lgkmcnt(3)
	v_mfma_f32_16x16x32_bf16 v[30:33], v[232:235], v[42:45], v[30:33]
	ds_read_b128 v[232:235], v156 offset:17408
	s_waitcnt lgkmcnt(3)
	v_mfma_f32_16x16x32_bf16 v[26:29], v[236:239], v[42:45], v[26:29]
	ds_read_b128 v[236:239], v157 offset:21760
	s_waitcnt lgkmcnt(3)
	v_mfma_f32_16x16x32_bf16 v[22:25], v[240:243], v[42:45], v[22:25]
	ds_read_b128 v[240:243], v158 offset:26112
	s_waitcnt lgkmcnt(3)
	v_mfma_f32_16x16x32_bf16 v[18:21], v[244:247], v[42:45], v[18:21]
	ds_read_b128 v[244:247], v159 offset:30464
	s_waitcnt lgkmcnt(3)
	v_mfma_f32_16x16x32_bf16 v[14:17], v[232:235], v[42:45], v[14:17]
	s_waitcnt lgkmcnt(2)
	v_mfma_f32_16x16x32_bf16 v[10:13], v[236:239], v[42:45], v[10:13]
	s_waitcnt lgkmcnt(1)
	v_mfma_f32_16x16x32_bf16 v[6:9], v[240:243], v[42:45], v[6:9]
	s_waitcnt lgkmcnt(0)
	v_mfma_f32_16x16x32_bf16 v[2:5], v[244:247], v[42:45], v[2:5]
	s_cbranch_vccnz .LBB0_922
	ds_read_b128 v[232:235], v160
	ds_read_b128 v[236:239], v161 offset:4352
	ds_read_b128 v[240:243], v162 offset:8704
	ds_read_b128 v[244:247], v163 offset:13056
	v_readlane_b32 s2, v249, 61
	v_readlane_b32 s3, v249, 62
	s_andn2_b64 vcc, exec, s[2:3]
	s_waitcnt lgkmcnt(3)
	v_mfma_f32_16x16x32_bf16 v[30:33], v[232:235], v[38:41], v[30:33]
	ds_read_b128 v[232:235], v164 offset:17408
	s_waitcnt lgkmcnt(3)
	v_mfma_f32_16x16x32_bf16 v[26:29], v[236:239], v[38:41], v[26:29]
	ds_read_b128 v[236:239], v165 offset:21760
	s_waitcnt lgkmcnt(3)
	v_mfma_f32_16x16x32_bf16 v[22:25], v[240:243], v[38:41], v[22:25]
	ds_read_b128 v[240:243], v166 offset:26112
	s_waitcnt lgkmcnt(3)
	v_mfma_f32_16x16x32_bf16 v[18:21], v[244:247], v[38:41], v[18:21]
	ds_read_b128 v[244:247], v167 offset:30464
	s_waitcnt lgkmcnt(3)
	v_mfma_f32_16x16x32_bf16 v[14:17], v[232:235], v[38:41], v[14:17]
	s_waitcnt lgkmcnt(2)
	v_mfma_f32_16x16x32_bf16 v[10:13], v[236:239], v[38:41], v[10:13]
	s_waitcnt lgkmcnt(1)
	v_mfma_f32_16x16x32_bf16 v[6:9], v[240:243], v[38:41], v[6:9]
	s_waitcnt lgkmcnt(0)
	v_mfma_f32_16x16x32_bf16 v[2:5], v[244:247], v[38:41], v[2:5]
	s_cbranch_vccnz .LBB0_922
	ds_read_b128 v[232:235], v168
	ds_read_b128 v[236:239], v169 offset:4352
	ds_read_b128 v[240:243], v170 offset:8704
	ds_read_b128 v[244:247], v171 offset:13056
	s_waitcnt lgkmcnt(3)
	v_mfma_f32_16x16x32_bf16 v[30:33], v[232:235], v[34:37], v[30:33]
	ds_read_b128 v[232:235], v172 offset:17408
	s_waitcnt lgkmcnt(3)
	v_mfma_f32_16x16x32_bf16 v[26:29], v[236:239], v[34:37], v[26:29]
	ds_read_b128 v[236:239], v173 offset:21760
	s_waitcnt lgkmcnt(3)
	v_mfma_f32_16x16x32_bf16 v[22:25], v[240:243], v[34:37], v[22:25]
	ds_read_b128 v[240:243], v174 offset:26112
	s_waitcnt lgkmcnt(3)
	v_mfma_f32_16x16x32_bf16 v[18:21], v[244:247], v[34:37], v[18:21]
	ds_read_b128 v[244:247], v175 offset:30464
	s_waitcnt lgkmcnt(3)
	v_mfma_f32_16x16x32_bf16 v[14:17], v[232:235], v[34:37], v[14:17]
	s_waitcnt lgkmcnt(2)
	v_mfma_f32_16x16x32_bf16 v[10:13], v[236:239], v[34:37], v[10:13]
	s_waitcnt lgkmcnt(1)
	v_mfma_f32_16x16x32_bf16 v[6:9], v[240:243], v[34:37], v[6:9]
	s_waitcnt lgkmcnt(0)
	v_mfma_f32_16x16x32_bf16 v[2:5], v[244:247], v[34:37], v[2:5]

; __device__ __forceinline__ void lru_fix_tile(const Ctx& C, int l, int ct, int hd) {
;     ...
;         if (T.c == 63 && t == 127) { float* o2 = C.out + O_LRUP + (size_t)(l * 2 + T.sidx) * GW + chg;
;             *(f32x4*)o2 = (f32x4){h[0], h[1], h[2], h[3]}; *(f32x4*)(o2 + 4) = (f32x4){h[4], h[5], h[6], h[7]}; }
;     }
;     __syncthreads();
.LBB0_1243:
	s_or_b64 exec, exec, s[24:25]
	s_and_b64 s[2:3], s[62:63], s[60:61]
	s_and_saveexec_b64 s[24:25], s[2:3]
	s_cbranch_execz .LBB0_910
	s_add_u32 s2, s7, s22
	s_addc_u32 s3, s92, s23
	global_store_dwordx4 v58, v[6:9], s[2:3]
	global_store_dwordx4 v58, v[2:5], s[2:3] offset:16
	s_branch .LBB0_910
	s_nop 0
	s_nop 0
	s_nop 0
	s_nop 0
	s_nop 0
	s_nop 0
	s_nop 0
	s_nop 0
	s_nop 0
	s_nop 0
	s_nop 0
	s_nop 0
	s_nop 0
	s_nop 0
